# v30 + prompt unit epilogue: sub-LayerNorm gain loads issued at the start of the epilogue
# baseline (speedup 1.0000x reference)
; #define LAS __attribute__((address_space(3)))
; #define GASP __attribute__((address_space(1)))
; __device__ __forceinline__ float frcp(float x) { return __builtin_amdgcn_rcpf(x); }
;     ...
;         const float inv = frcp(l);
;         LAS float* X = (LAS float*)L + sub * 4096;
;         if (map == 1) {
; #pragma unroll
;             for (int eb = 0; eb < 4; ++eb)
; #pragma unroll
;                 for (int rg = 0; rg < 16; ++rg) X[(eb * 32 + (rg & 3) + 8 * (rg >> 2) + 4 * hi) * 32 + r] = OT[eb][rg] * inv;
;         }
;     ...
;             const float* sg = p.in[16];
;             bf16_t* op = (bf16_t*)(ws + O_MIX) + (size_t)(rowq0 + r) * D + h * 128 + 4 * hi;
; #pragma unroll
;             for (int eb = 0; eb < 4; ++eb)
; #pragma unroll
;                 for (int g4 = 0; g4 < 4; ++g4) { const int e0 = eb * 32 + 8 * g4; const f32x4 gv = *(const GASP f32x4*)(sg + e0 + 4 * hi);
.LBB0_939:
	v_lshlrev_b32_e32 v243, 2, v147
	global_load_dwordx4 v[210:213], v243, s[16:17] offset:32
	global_load_dwordx4 v[214:217], v243, s[16:17] offset:64
	global_load_dwordx4 v[218:221], v243, s[16:17] offset:96
	global_load_dwordx4 v[222:225], v243, s[16:17] offset:128
	global_load_dwordx4 v[226:229], v243, s[16:17] offset:160
	global_load_dwordx4 v[230:233], v243, s[16:17] offset:192
	global_load_dwordx4 v[234:237], v243, s[16:17] offset:224
	global_load_dwordx4 v[238:241], v243, s[16:17] offset:256
	global_load_dwordx4 v[244:247], v243, s[16:17] offset:288
	global_load_dwordx4 v[248:251], v243, s[16:17] offset:320
	global_load_dwordx4 v[176:179], v243, s[16:17] offset:352
	global_load_dwordx4 v[180:183], v243, s[16:17] offset:384
	global_load_dwordx4 v[184:187], v243, s[16:17] offset:416
	global_load_dwordx4 v[188:191], v243, s[16:17] offset:448
	global_load_dwordx4 v[166:169], v243, s[16:17] offset:480
	ds_bpermute_b32 v0, v171, v159
	s_lshl_b32 s6, s10, 14
	s_add_i32 s6, s6, 0
	v_lshlrev_b32_e32 v66, 2, v149
	v_lshlrev_b32_e32 v67, 9, v152
	s_waitcnt lgkmcnt(0)
	v_add_f32_e32 v0, v159, v0
	v_rcp_f32_e32 v0, v0
	s_cmp_lg_u32 s9, 1
	v_add3_u32 v66, s6, v66, v67
	s_cbranch_scc1 .LBB0_941
	v_mul_f32_e32 v67, v50, v0
	v_mul_f32_e32 v68, v51, v0
	ds_write2_b32 v66, v67, v68 offset1:32
	v_mul_f32_e32 v67, v52, v0
	v_mul_f32_e32 v68, v53, v0
	ds_write2_b32 v66, v67, v68 offset0:64 offset1:96
	v_mul_f32_e32 v67, v54, v0
	v_mul_f32_e32 v68, v55, v0
	v_add_u32_e32 v69, 0x400, v66
	ds_write2_b32 v69, v67, v68 offset1:32
	v_mul_f32_e32 v67, v56, v0
	v_mul_f32_e32 v68, v57, v0
	ds_write2_b32 v69, v67, v68 offset0:64 offset1:96
	v_mul_f32_e32 v67, v58, v0
	v_mul_f32_e32 v68, v59, v0
	v_add_u32_e32 v69, 0x800, v66
	ds_write2_b32 v69, v67, v68 offset1:32
	v_mul_f32_e32 v67, v60, v0
	v_mul_f32_e32 v68, v61, v0
	ds_write2_b32 v69, v67, v68 offset0:64 offset1:96
	v_mul_f32_e32 v67, v62, v0
	v_mul_f32_e32 v68, v63, v0
	v_add_u32_e32 v69, 0xc00, v66
	ds_write2_b32 v69, v67, v68 offset1:32
	v_mul_f32_e32 v67, v64, v0
	v_mul_f32_e32 v68, v65, v0
	ds_write2_b32 v69, v67, v68 offset0:64 offset1:96
	v_mul_f32_e32 v67, v34, v0
	v_mul_f32_e32 v68, v35, v0
	v_add_u32_e32 v69, 0x1000, v66
	ds_write2_b32 v69, v67, v68 offset1:32
	v_mul_f32_e32 v67, v36, v0
	v_mul_f32_e32 v68, v37, v0
	ds_write2_b32 v69, v67, v68 offset0:64 offset1:96
	v_mul_f32_e32 v67, v38, v0
	v_mul_f32_e32 v68, v39, v0
	v_add_u32_e32 v69, 0x1400, v66
	ds_write2_b32 v69, v67, v68 offset1:32
	v_mul_f32_e32 v67, v40, v0
	v_mul_f32_e32 v68, v41, v0
	ds_write2_b32 v69, v67, v68 offset0:64 offset1:96
	v_mul_f32_e32 v67, v42, v0
	v_mul_f32_e32 v68, v43, v0
	v_add_u32_e32 v69, 0x1800, v66
	ds_write2_b32 v69, v67, v68 offset1:32
	v_mul_f32_e32 v67, v44, v0
	v_mul_f32_e32 v68, v45, v0
	ds_write2_b32 v69, v67, v68 offset0:64 offset1:96
	v_mul_f32_e32 v67, v46, v0
	v_mul_f32_e32 v68, v47, v0
	v_add_u32_e32 v69, 0x1c00, v66
	ds_write2_b32 v69, v67, v68 offset1:32
	v_mul_f32_e32 v67, v48, v0
	v_mul_f32_e32 v68, v49, v0
	ds_write2_b32 v69, v67, v68 offset0:64 offset1:96
	v_mul_f32_e32 v67, v18, v0
	v_mul_f32_e32 v68, v19, v0
	v_add_u32_e32 v69, 0x2000, v66
	ds_write2_b32 v69, v67, v68 offset1:32
	v_mul_f32_e32 v67, v20, v0
	v_mul_f32_e32 v68, v21, v0
	ds_write2_b32 v69, v67, v68 offset0:64 offset1:96
	v_mul_f32_e32 v67, v22, v0
	v_mul_f32_e32 v68, v23, v0
	v_add_u32_e32 v69, 0x2400, v66
	ds_write2_b32 v69, v67, v68 offset1:32
	v_mul_f32_e32 v67, v24, v0
	v_mul_f32_e32 v68, v25, v0
	ds_write2_b32 v69, v67, v68 offset0:64 offset1:96
	v_mul_f32_e32 v67, v26, v0
	v_mul_f32_e32 v68, v27, v0
	v_add_u32_e32 v69, 0x2800, v66
	ds_write2_b32 v69, v67, v68 offset1:32
	v_mul_f32_e32 v67, v28, v0
	v_mul_f32_e32 v68, v29, v0
	ds_write2_b32 v69, v67, v68 offset0:64 offset1:96
	v_mul_f32_e32 v67, v30, v0
	v_mul_f32_e32 v68, v31, v0
	v_add_u32_e32 v69, 0x2c00, v66
	ds_write2_b32 v69, v67, v68 offset1:32
	v_mul_f32_e32 v67, v32, v0
	v_mul_f32_e32 v68, v33, v0
	ds_write2_b32 v69, v67, v68 offset0:64 offset1:96
	v_mul_f32_e32 v67, v2, v0
	v_mul_f32_e32 v68, v3, v0
	v_add_u32_e32 v69, 0x3000, v66
	ds_write2_b32 v69, v67, v68 offset1:32
	v_mul_f32_e32 v67, v4, v0
	v_mul_f32_e32 v68, v5, v0
	ds_write2_b32 v69, v67, v68 offset0:64 offset1:96
	v_mul_f32_e32 v67, v6, v0
	v_mul_f32_e32 v68, v7, v0
	v_add_u32_e32 v69, 0x3400, v66
	ds_write2_b32 v69, v67, v68 offset1:32
	v_mul_f32_e32 v67, v8, v0
	v_mul_f32_e32 v68, v9, v0
	ds_write2_b32 v69, v67, v68 offset0:64 offset1:96
	v_mul_f32_e32 v67, v10, v0
	v_mul_f32_e32 v68, v11, v0
	v_add_u32_e32 v69, 0x3800, v66
	ds_write2_b32 v69, v67, v68 offset1:32
	v_mul_f32_e32 v67, v12, v0
	v_mul_f32_e32 v68, v13, v0
	ds_write2_b32 v69, v67, v68 offset0:64 offset1:96
	v_mul_f32_e32 v67, v14, v0
	v_mul_f32_e32 v68, v15, v0
	v_add_u32_e32 v69, 0x3c00, v66
	ds_write2_b32 v69, v67, v68 offset1:32
	v_mul_f32_e32 v67, v16, v0
	v_mul_f32_e32 v68, v17, v0
	ds_write2_b32 v69, v67, v68 offset0:64 offset1:96
;     ...
;         __syncthreads();
;         if (map == 0) {
;             float ss = 0.f;
; #pragma unroll
;             for (int eb = 0; eb < 4; ++eb)
; #pragma unroll
;                 for (int rg = 0; rg < 16; ++rg) { const float o = OT[eb][rg] * inv - lam * X[(eb * 32 + (rg & 3) + 8 * (rg >> 2) + 4 * hi) * 32 + r]; OT[eb][rg] = o; ss += o * o; }
.LBB0_941:
	s_cmpk_gt_u32 s8, 0xff
	s_waitcnt lgkmcnt(0)
	s_barrier
	s_cbranch_scc1 .LBB0_943
	v_add_u32_e32 v67, 0x400, v66
	ds_read2_b32 v[70:71], v66 offset1:32
	ds_read2_b32 v[72:73], v66 offset0:64 offset1:96
	ds_read2_b32 v[74:75], v67 offset1:32
	ds_read2_b32 v[76:77], v67 offset0:64 offset1:96
	v_add_u32_e32 v67, 0x800, v66
	ds_read2_b32 v[84:85], v67 offset1:32
	ds_read2_b32 v[86:87], v67 offset0:64 offset1:96
	v_add_u32_e32 v67, 0xc00, v66
	ds_read2_b32 v[88:89], v67 offset1:32
	ds_read2_b32 v[90:91], v67 offset0:64 offset1:96
	v_add_u32_e32 v67, 0x1000, v66
	ds_read2_b32 v[92:93], v67 offset1:32
	ds_read2_b32 v[94:95], v67 offset0:64 offset1:96
	v_add_u32_e32 v67, 0x1400, v66
	ds_read2_b32 v[96:97], v67 offset1:32
	ds_read2_b32 v[98:99], v67 offset0:64 offset1:96
	v_add_u32_e32 v67, 0x1800, v66
	s_waitcnt lgkmcnt(11)
	v_pk_mul_f32 v[70:71], v[160:161], v[70:71]
	ds_read2_b32 v[100:101], v67 offset1:32
	ds_read2_b32 v[102:103], v67 offset0:64 offset1:96
	v_add_u32_e32 v67, 0x1c00, v66
	v_pk_fma_f32 v[70:71], v[50:51], v[0:1], v[70:71] op_sel_hi:[1,0,1] neg_lo:[0,0,1] neg_hi:[0,0,1]
	s_waitcnt lgkmcnt(10)
	v_pk_mul_f32 v[50:51], v[160:161], v[76:77]
	ds_read2_b32 v[104:105], v67 offset1:32
	ds_read2_b32 v[106:107], v67 offset0:64 offset1:96
	v_add_u32_e32 v67, 0x2000, v66
	v_pk_mul_f32 v[72:73], v[160:161], v[72:73]
	v_pk_fma_f32 v[50:51], v[56:57], v[0:1], v[50:51] op_sel_hi:[1,0,1] neg_lo:[0,0,1] neg_hi:[0,0,1]
	v_pk_mul_f32 v[56:57], v[160:161], v[74:75]
	ds_read2_b32 v[108:109], v67 offset1:32
	ds_read2_b32 v[110:111], v67 offset0:64 offset1:96
	v_add_u32_e32 v67, 0x2400, v66
	v_pk_fma_f32 v[52:53], v[52:53], v[0:1], v[72:73] op_sel_hi:[1,0,1] neg_lo:[0,0,1] neg_hi:[0,0,1]
	v_pk_fma_f32 v[72:73], v[54:55], v[0:1], v[56:57] op_sel_hi:[1,0,1] neg_lo:[0,0,1] neg_hi:[0,0,1]
	s_waitcnt lgkmcnt(13)
	v_pk_mul_f32 v[56:57], v[160:161], v[84:85]
	ds_read2_b32 v[112:113], v67 offset1:32
	s_waitcnt vmcnt(3)
	ds_read2_b32 v[114:115], v67 offset0:64 offset1:96
	v_add_u32_e32 v67, 0x2800, v66
	v_pk_fma_f32 v[74:75], v[58:59], v[0:1], v[56:57] op_sel_hi:[1,0,1] neg_lo:[0,0,1] neg_hi:[0,0,1]
	s_waitcnt lgkmcnt(13)
	v_pk_mul_f32 v[58:59], v[160:161], v[88:89]
	ds_read2_b32 v[116:117], v67 offset1:32
	s_waitcnt vmcnt(2)
	ds_read2_b32 v[118:119], v67 offset0:64 offset1:96
	v_add_u32_e32 v67, 0x2c00, v66
	v_pk_fma_f32 v[76:77], v[62:63], v[0:1], v[58:59] op_sel_hi:[1,0,1] neg_lo:[0,0,1] neg_hi:[0,0,1]
	s_waitcnt lgkmcnt(12)
	v_pk_mul_f32 v[58:59], v[160:161], v[94:95]
	ds_read2_b32 v[120:121], v67 offset1:32
	s_waitcnt vmcnt(1)
	ds_read2_b32 v[122:123], v67 offset0:64 offset1:96
	v_add_u32_e32 v67, 0x3000, v66
	v_pk_mul_f32 v[54:55], v[160:161], v[86:87]
	v_pk_fma_f32 v[58:59], v[36:37], v[0:1], v[58:59] op_sel_hi:[1,0,1] neg_lo:[0,0,1] neg_hi:[0,0,1]
	v_pk_mul_f32 v[36:37], v[160:161], v[92:93]
	ds_read2_b32 v[124:125], v67 offset1:32
	s_waitcnt vmcnt(0)
	ds_read2_b32 v[126:127], v67 offset0:64 offset1:96
	v_add_u32_e32 v67, 0x3400, v66
	v_add_u32_e32 v78, 0x3800, v66
	v_pk_fma_f32 v[54:55], v[60:61], v[0:1], v[54:55] op_sel_hi:[1,0,1] neg_lo:[0,0,1] neg_hi:[0,0,1]
	v_pk_fma_f32 v[60:61], v[34:35], v[0:1], v[36:37] op_sel_hi:[1,0,1] neg_lo:[0,0,1] neg_hi:[0,0,1]
	s_waitcnt lgkmcnt(14)
	v_pk_mul_f32 v[34:35], v[160:161], v[98:99]
	ds_read2_b32 v[128:129], v67 offset1:32
	ds_read2_b32 v[68:69], v78 offset0:64 offset1:96
	ds_read2_b32 v[130:131], v67 offset0:64 offset1:96
	ds_read2_b32 v[132:133], v78 offset1:32
	v_pk_fma_f32 v[34:35], v[40:41], v[0:1], v[34:35] op_sel_hi:[1,0,1] neg_lo:[0,0,1] neg_hi:[0,0,1]
	s_waitcnt lgkmcnt(14)
	v_pk_mul_f32 v[40:41], v[160:161], v[104:105]
	v_pk_mul_f32 v[36:37], v[160:161], v[96:97]
	v_pk_fma_f32 v[46:47], v[46:47], v[0:1], v[40:41] op_sel_hi:[1,0,1] neg_lo:[0,0,1] neg_hi:[0,0,1]
	s_waitcnt lgkmcnt(12)
	v_pk_mul_f32 v[40:41], v[160:161], v[110:111]
	v_pk_mul_f32 v[56:57], v[160:161], v[90:91]
	v_pk_fma_f32 v[62:63], v[38:39], v[0:1], v[36:37] op_sel_hi:[1,0,1] neg_lo:[0,0,1] neg_hi:[0,0,1]
	v_pk_mul_f32 v[38:39], v[160:161], v[100:101]
	v_pk_fma_f32 v[40:41], v[20:21], v[0:1], v[40:41] op_sel_hi:[1,0,1] neg_lo:[0,0,1] neg_hi:[0,0,1]
	v_pk_mul_f32 v[20:21], v[160:161], v[108:109]
	v_add_u32_e32 v78, 0x3c00, v66
	s_waitcnt lgkmcnt(2)
	v_pk_mul_f32 v[66:67], v[160:161], v[68:69]
	v_pk_fma_f32 v[56:57], v[64:65], v[0:1], v[56:57] op_sel_hi:[1,0,1] neg_lo:[0,0,1] neg_hi:[0,0,1]
	v_pk_mul_f32 v[36:37], v[160:161], v[102:103]
	v_pk_fma_f32 v[64:65], v[42:43], v[0:1], v[38:39] op_sel_hi:[1,0,1] neg_lo:[0,0,1] neg_hi:[0,0,1]
	v_pk_fma_f32 v[42:43], v[18:19], v[0:1], v[20:21] op_sel_hi:[1,0,1] neg_lo:[0,0,1] neg_hi:[0,0,1]
	v_pk_mul_f32 v[18:19], v[160:161], v[114:115]
	v_pk_mul_f32 v[20:21], v[160:161], v[112:113]
	ds_read2_b32 v[80:81], v78 offset1:32
	v_pk_fma_f32 v[66:67], v[12:13], v[0:1], v[66:67] op_sel_hi:[1,0,1] neg_lo:[0,0,1] neg_hi:[0,0,1]
	ds_read2_b32 v[12:13], v78 offset0:64 offset1:96
	v_pk_fma_f32 v[36:37], v[44:45], v[0:1], v[36:37] op_sel_hi:[1,0,1] neg_lo:[0,0,1] neg_hi:[0,0,1]
	v_pk_fma_f32 v[18:19], v[24:25], v[0:1], v[18:19] op_sel_hi:[1,0,1] neg_lo:[0,0,1] neg_hi:[0,0,1]
	v_pk_fma_f32 v[44:45], v[22:23], v[0:1], v[20:21] op_sel_hi:[1,0,1] neg_lo:[0,0,1] neg_hi:[0,0,1]
	v_pk_mul_f32 v[20:21], v[160:161], v[118:119]
	v_pk_mul_f32 v[24:25], v[160:161], v[120:121]
	v_pk_fma_f32 v[20:21], v[28:29], v[0:1], v[20:21] op_sel_hi:[1,0,1] neg_lo:[0,0,1] neg_hi:[0,0,1]
	v_pk_fma_f32 v[28:29], v[30:31], v[0:1], v[24:25] op_sel_hi:[1,0,1] neg_lo:[0,0,1] neg_hi:[0,0,1]
	v_pk_mul_f32 v[24:25], v[160:161], v[126:127]
	v_pk_mul_f32 v[22:23], v[160:161], v[116:117]
	v_pk_fma_f32 v[4:5], v[4:5], v[0:1], v[24:25] op_sel_hi:[1,0,1] neg_lo:[0,0,1] neg_hi:[0,0,1]
	v_pk_mul_f32 v[24:25], v[160:161], v[124:125]
	s_waitcnt lgkmcnt(1)
; #define GASP __attribute__((address_space(1)))
;     ...
;             float ss = 0.f;
; #pragma unroll
;             for (int eb = 0; eb < 4; ++eb)
; #pragma unroll
;                 for (int rg = 0; rg < 16; ++rg) { const float o = OT[eb][rg] * inv - lam * X[(eb * 32 + (rg & 3) + 8 * (rg >> 2) + 4 * hi) * 32 + r]; OT[eb][rg] = o; ss += o * o; }
;             ss += __shfl_xor(ss, 32);
;             const float rms = 0.8f / sqrtf(ss * (1.f / 128.f) + LN_EPS);
;             const float* sg = p.in[16];
;             bf16_t* op = (bf16_t*)(ws + O_MIX) + (size_t)(rowq0 + r) * D + h * 128 + 4 * hi;
; #pragma unroll
;             for (int eb = 0; eb < 4; ++eb)
; #pragma unroll
;                 for (int g4 = 0; g4 < 4; ++g4) { const int e0 = eb * 32 + 8 * g4; const f32x4 gv = *(const GASP f32x4*)(sg + e0 + 4 * hi);
	v_pk_mul_f32 v[68:69], v[160:161], v[80:81]
	v_pk_fma_f32 v[24:25], v[2:3], v[0:1], v[24:25] op_sel_hi:[1,0,1] neg_lo:[0,0,1] neg_hi:[0,0,1]
	v_pk_mul_f32 v[2:3], v[160:161], v[130:131]
	s_waitcnt lgkmcnt(0)
	v_pk_mul_f32 v[12:13], v[160:161], v[12:13]
	v_pk_fma_f32 v[2:3], v[8:9], v[0:1], v[2:3] op_sel_hi:[1,0,1] neg_lo:[0,0,1] neg_hi:[0,0,1]
	v_pk_mul_f32 v[8:9], v[160:161], v[128:129]
	v_pk_mul_f32 v[136:137], v[70:71], v[70:71]
	v_pk_mul_f32 v[38:39], v[160:161], v[106:107]
	v_pk_fma_f32 v[26:27], v[26:27], v[0:1], v[22:23] op_sel_hi:[1,0,1] neg_lo:[0,0,1] neg_hi:[0,0,1]
	v_pk_mul_f32 v[22:23], v[160:161], v[122:123]
	v_pk_fma_f32 v[8:9], v[6:7], v[0:1], v[8:9] op_sel_hi:[1,0,1] neg_lo:[0,0,1] neg_hi:[0,0,1]
	v_pk_mul_f32 v[6:7], v[160:161], v[132:133]
	v_pk_fma_f32 v[68:69], v[14:15], v[0:1], v[68:69] op_sel_hi:[1,0,1] neg_lo:[0,0,1] neg_hi:[0,0,1]
	v_pk_fma_f32 v[16:17], v[16:17], v[0:1], v[12:13] op_sel_hi:[1,0,1] neg_lo:[0,0,1] neg_hi:[0,0,1]
	v_pk_mul_f32 v[134:135], v[52:53], v[52:53]
	v_pk_fma_f32 v[38:39], v[48:49], v[0:1], v[38:39] op_sel_hi:[1,0,1] neg_lo:[0,0,1] neg_hi:[0,0,1]
	v_pk_fma_f32 v[22:23], v[32:33], v[0:1], v[22:23] op_sel_hi:[1,0,1] neg_lo:[0,0,1] neg_hi:[0,0,1]
	v_pk_fma_f32 v[6:7], v[10:11], v[0:1], v[6:7] op_sel_hi:[1,0,1] neg_lo:[0,0,1] neg_hi:[0,0,1]
	v_add_f32_e32 v0, v136, v137
	v_add_f32_e32 v0, v0, v134
	v_pk_mul_f32 v[140:141], v[72:73], v[72:73]
	v_add_f32_e32 v0, v0, v135
	v_add_f32_e32 v0, v0, v140
	v_pk_mul_f32 v[138:139], v[50:51], v[50:51]
	v_add_f32_e32 v0, v0, v141
	v_add_f32_e32 v0, v0, v138
	v_pk_mul_f32 v[84:85], v[74:75], v[74:75]
	v_add_f32_e32 v0, v0, v139
	v_add_f32_e32 v0, v0, v84
	v_pk_mul_f32 v[86:87], v[54:55], v[54:55]
	v_add_f32_e32 v0, v0, v85
	v_add_f32_e32 v0, v0, v86
	v_pk_mul_f32 v[88:89], v[76:77], v[76:77]
	v_add_f32_e32 v0, v0, v87
	v_add_f32_e32 v0, v0, v88
	v_pk_mul_f32 v[90:91], v[56:57], v[56:57]
	v_add_f32_e32 v0, v0, v89
	v_add_f32_e32 v0, v0, v90
	v_pk_mul_f32 v[92:93], v[60:61], v[60:61]
	v_add_f32_e32 v0, v0, v91
	v_add_f32_e32 v0, v0, v92
	v_pk_mul_f32 v[94:95], v[58:59], v[58:59]
	v_add_f32_e32 v0, v0, v93
	v_add_f32_e32 v0, v0, v94
	v_lshlrev_b32_e32 v142, 2, v147
	v_pk_mul_f32 v[96:97], v[62:63], v[62:63]
	v_add_f32_e32 v0, v0, v95
	global_load_dwordx4 v[12:15], v142, s[16:17]
	v_add_f32_e32 v0, v0, v96
	v_pk_mul_f32 v[98:99], v[34:35], v[34:35]
	v_add_f32_e32 v0, v0, v97
	v_add_f32_e32 v0, v0, v98
	v_pk_mul_f32 v[100:101], v[64:65], v[64:65]
	v_add_f32_e32 v0, v0, v99
	v_add_f32_e32 v0, v0, v100
	v_pk_mul_f32 v[102:103], v[36:37], v[36:37]
	v_add_f32_e32 v0, v0, v101
	v_add_f32_e32 v0, v0, v102
	v_pk_mul_f32 v[104:105], v[46:47], v[46:47]
	v_add_f32_e32 v0, v0, v103
	v_add_f32_e32 v0, v0, v104
	v_pk_mul_f32 v[48:49], v[38:39], v[38:39]
	v_add_f32_e32 v0, v0, v105
	v_add_f32_e32 v0, v0, v48
	v_pk_mul_f32 v[108:109], v[42:43], v[42:43]
	v_add_f32_e32 v0, v0, v49
	v_add_f32_e32 v0, v0, v108
	v_pk_mul_f32 v[106:107], v[40:41], v[40:41]
	v_add_f32_e32 v0, v0, v109
	v_add_f32_e32 v0, v0, v106
	v_pk_mul_f32 v[112:113], v[44:45], v[44:45]
	v_add_f32_e32 v0, v0, v107
	v_add_f32_e32 v0, v0, v112
	v_pk_mul_f32 v[110:111], v[18:19], v[18:19]
	v_add_f32_e32 v0, v0, v113
	v_add_f32_e32 v0, v0, v110
	v_pk_mul_f32 v[116:117], v[26:27], v[26:27]
	v_add_f32_e32 v0, v0, v111
	v_add_f32_e32 v0, v0, v116
	v_pk_mul_f32 v[114:115], v[20:21], v[20:21]
	v_add_f32_e32 v0, v0, v117
	v_add_f32_e32 v0, v0, v114
	v_pk_mul_f32 v[30:31], v[28:29], v[28:29]
	v_add_f32_e32 v0, v0, v115
	v_add_f32_e32 v0, v0, v30
	v_pk_mul_f32 v[32:33], v[22:23], v[22:23]
	v_add_f32_e32 v0, v0, v31
	v_add_f32_e32 v0, v0, v32
	v_pk_mul_f32 v[120:121], v[24:25], v[24:25]
	v_add_f32_e32 v0, v0, v33
	v_add_f32_e32 v0, v0, v120
	v_pk_mul_f32 v[118:119], v[4:5], v[4:5]
	v_add_f32_e32 v0, v0, v121
	v_add_f32_e32 v0, v0, v118
	v_pk_mul_f32 v[124:125], v[8:9], v[8:9]
	v_add_f32_e32 v0, v0, v119
	v_add_f32_e32 v0, v0, v124
	v_pk_mul_f32 v[122:123], v[2:3], v[2:3]
	v_add_f32_e32 v0, v0, v125
	v_add_f32_e32 v0, v0, v122
	v_pk_mul_f32 v[10:11], v[6:7], v[6:7]
	v_add_f32_e32 v0, v0, v123
	v_add_f32_e32 v0, v0, v10
	v_pk_mul_f32 v[78:79], v[66:67], v[66:67]
	v_add_f32_e32 v0, v0, v11
	v_add_f32_e32 v0, v0, v78
	v_pk_mul_f32 v[80:81], v[68:69], v[68:69]
	v_add_f32_e32 v0, v0, v79
	v_add_f32_e32 v0, v0, v80
	v_pk_mul_f32 v[82:83], v[16:17], v[16:17]
	v_add_f32_e32 v0, v0, v81
	v_add_f32_e32 v0, v0, v82
	v_add_f32_e32 v0, v0, v83
	ds_bpermute_b32 v10, v171, v0
	s_lshl_b32 s30, s5, 1
	s_waitcnt lgkmcnt(0)
	v_add_f32_e32 v0, v0, v10
	v_fmamk_f32 v0, v0, 0x3c000000, v172
	v_mul_f32_e32 v10, 0x4f800000, v0
	v_cmp_gt_f32_e32 vcc, s35, v0
	s_nop 1
	v_cndmask_b32_e32 v30, v0, v10, vcc
	v_sqrt_f32_e32 v31, v30
	v_lshlrev_b32_e32 v0, 11, v146
	v_lshl_add_u64 v[10:11], s[76:77], 0, v[0:1]
	v_lshl_add_u64 v[10:11], v[10:11], 0, s[30:31]
	v_add_u32_e32 v0, -1, v31
	v_fma_f32 v32, -v0, v31, v30
	v_cmp_ge_f32_e64 s[6:7], 0, v32
	v_add_u32_e32 v32, 1, v31
	s_nop 0
	v_cndmask_b32_e64 v0, v31, v0, s[6:7]
	v_fma_f32 v31, -v32, v31, v30
	v_cmp_lt_f32_e64 s[6:7], 0, v31
	s_nop 1
	v_cndmask_b32_e64 v0, v0, v32, s[6:7]
	v_mul_f32_e32 v31, 0x37800000, v0
	v_cndmask_b32_e32 v0, v0, v31, vcc
	v_cmp_class_f32_e32 vcc, v30, v170
	s_nop 1
	v_cndmask_b32_e32 v32, v0, v30, vcc
	v_div_scale_f32 v33, s[6:7], v32, v32, s1
	v_rcp_f32_e32 v48, v33
	v_lshlrev_b32_e32 v0, 1, v147
	v_lshl_add_u64 v[30:31], v[10:11], 0, v[0:1]
	v_fma_f32 v0, -v33, v48, 1.0
	v_fmac_f32_e32 v48, v0, v48
	v_div_scale_f32 v0, vcc, s1, v32, s1
	v_mul_f32_e32 v10, v0, v48
	v_fma_f32 v11, -v33, v10, v0
	v_fmac_f32_e32 v10, v11, v48
	v_fma_f32 v0, -v33, v10, v0
	v_div_fmas_f32 v0, v0, v48, v10
	v_div_fixup_f32 v0, v0, v32, s1
	s_waitcnt vmcnt(0)
; #define GASP __attribute__((address_space(1)))
;     ...
;             const float* sg = p.in[16];
;             bf16_t* op = (bf16_t*)(ws + O_MIX) + (size_t)(rowq0 + r) * D + h * 128 + 4 * hi;
; #pragma unroll
;             for (int eb = 0; eb < 4; ++eb)
; #pragma unroll
;                 for (int g4 = 0; g4 < 4; ++g4) { const int e0 = eb * 32 + 8 * g4; const f32x4 gv = *(const GASP f32x4*)(sg + e0 + 4 * hi);
;                     u32x2 w; w.x = pk2(OT[eb][4 * g4] * rms * gv[0], OT[eb][4 * g4 + 1] * rms * gv[1]); w.y = pk2(OT[eb][4 * g4 + 2] * rms * gv[2], OT[eb][4 * g4 + 3] * rms * gv[3]);
;                     *(GASP u32x2*)(op + e0) = w; }
	v_lshlrev_b32_e32 v202, 1, v147
	v_mov_b32_e32 v203, 0
	v_lshl_add_u64 v[206:207], v[30:31], 0, v[202:203]
	v_pk_mul_f32 v[202:203], v[70:71], v[0:1] op_sel_hi:[1,0]
	v_pk_mul_f32 v[204:205], v[52:53], v[0:1] op_sel_hi:[1,0]
	v_pk_mul_f32 v[202:203], v[12:13], v[202:203]
	v_pk_mul_f32 v[204:205], v[14:15], v[204:205]
	s_nop 0
	v_cvt_pk_bf16_f32 v194, v202, v203
	v_cvt_pk_bf16_f32 v195, v204, v205
	v_pk_mul_f32 v[202:203], v[72:73], v[0:1] op_sel_hi:[1,0]
	v_pk_mul_f32 v[204:205], v[50:51], v[0:1] op_sel_hi:[1,0]
	v_pk_mul_f32 v[202:203], v[210:211], v[202:203]
	v_pk_mul_f32 v[204:205], v[212:213], v[204:205]
	s_nop 0
	v_cvt_pk_bf16_f32 v196, v202, v203
	v_cvt_pk_bf16_f32 v197, v204, v205
	s_nop 1
	v_permlane32_swap_b32_e32 v194, v196
	v_permlane32_swap_b32_e32 v195, v197
	global_store_dwordx4 v[206:207], v[194:197], off
	v_pk_mul_f32 v[202:203], v[74:75], v[0:1] op_sel_hi:[1,0]
	v_pk_mul_f32 v[204:205], v[54:55], v[0:1] op_sel_hi:[1,0]
	v_pk_mul_f32 v[202:203], v[214:215], v[202:203]
	v_pk_mul_f32 v[204:205], v[216:217], v[204:205]
	s_nop 0
	v_cvt_pk_bf16_f32 v198, v202, v203
	v_cvt_pk_bf16_f32 v199, v204, v205
	v_pk_mul_f32 v[202:203], v[76:77], v[0:1] op_sel_hi:[1,0]
	v_pk_mul_f32 v[204:205], v[56:57], v[0:1] op_sel_hi:[1,0]
	v_pk_mul_f32 v[202:203], v[218:219], v[202:203]
	v_pk_mul_f32 v[204:205], v[220:221], v[204:205]
	s_nop 0
	v_cvt_pk_bf16_f32 v200, v202, v203
	v_cvt_pk_bf16_f32 v201, v204, v205
	s_nop 1
	v_permlane32_swap_b32_e32 v198, v200
	v_permlane32_swap_b32_e32 v199, v201
	global_store_dwordx4 v[206:207], v[198:201], off offset:32
	v_pk_mul_f32 v[202:203], v[60:61], v[0:1] op_sel_hi:[1,0]
	v_pk_mul_f32 v[204:205], v[58:59], v[0:1] op_sel_hi:[1,0]
	v_pk_mul_f32 v[202:203], v[222:223], v[202:203]
	v_pk_mul_f32 v[204:205], v[224:225], v[204:205]
	s_nop 0
	v_cvt_pk_bf16_f32 v194, v202, v203
	v_cvt_pk_bf16_f32 v195, v204, v205
	v_pk_mul_f32 v[202:203], v[62:63], v[0:1] op_sel_hi:[1,0]
	v_pk_mul_f32 v[204:205], v[34:35], v[0:1] op_sel_hi:[1,0]
	v_pk_mul_f32 v[202:203], v[226:227], v[202:203]
	v_pk_mul_f32 v[204:205], v[228:229], v[204:205]
	s_nop 0
	v_cvt_pk_bf16_f32 v196, v202, v203
	v_cvt_pk_bf16_f32 v197, v204, v205
	s_nop 1
	v_permlane32_swap_b32_e32 v194, v196
	v_permlane32_swap_b32_e32 v195, v197
	global_store_dwordx4 v[206:207], v[194:197], off offset:64
	v_pk_mul_f32 v[202:203], v[64:65], v[0:1] op_sel_hi:[1,0]
	v_pk_mul_f32 v[204:205], v[36:37], v[0:1] op_sel_hi:[1,0]
	v_pk_mul_f32 v[202:203], v[230:231], v[202:203]
	v_pk_mul_f32 v[204:205], v[232:233], v[204:205]
	s_nop 0
	v_cvt_pk_bf16_f32 v198, v202, v203
	v_cvt_pk_bf16_f32 v199, v204, v205
	v_pk_mul_f32 v[202:203], v[46:47], v[0:1] op_sel_hi:[1,0]
	v_pk_mul_f32 v[204:205], v[38:39], v[0:1] op_sel_hi:[1,0]
	v_pk_mul_f32 v[202:203], v[234:235], v[202:203]
	v_pk_mul_f32 v[204:205], v[236:237], v[204:205]
	s_nop 0
	v_cvt_pk_bf16_f32 v200, v202, v203
	v_cvt_pk_bf16_f32 v201, v204, v205
	s_nop 1
	v_permlane32_swap_b32_e32 v198, v200
	v_permlane32_swap_b32_e32 v199, v201
	global_store_dwordx4 v[206:207], v[198:201], off offset:96
	v_pk_mul_f32 v[202:203], v[42:43], v[0:1] op_sel_hi:[1,0]
	v_pk_mul_f32 v[204:205], v[40:41], v[0:1] op_sel_hi:[1,0]
	v_pk_mul_f32 v[202:203], v[238:239], v[202:203]
	v_pk_mul_f32 v[204:205], v[240:241], v[204:205]
	s_nop 0
	v_cvt_pk_bf16_f32 v194, v202, v203
	v_cvt_pk_bf16_f32 v195, v204, v205
	v_pk_mul_f32 v[202:203], v[44:45], v[0:1] op_sel_hi:[1,0]
	v_pk_mul_f32 v[204:205], v[18:19], v[0:1] op_sel_hi:[1,0]
	v_pk_mul_f32 v[202:203], v[244:245], v[202:203]
	v_pk_mul_f32 v[204:205], v[246:247], v[204:205]
	s_nop 0
	v_cvt_pk_bf16_f32 v196, v202, v203
	v_cvt_pk_bf16_f32 v197, v204, v205
	s_nop 1
	v_permlane32_swap_b32_e32 v194, v196
	v_permlane32_swap_b32_e32 v195, v197
	global_store_dwordx4 v[206:207], v[194:197], off offset:128
	v_pk_mul_f32 v[202:203], v[26:27], v[0:1] op_sel_hi:[1,0]
	v_pk_mul_f32 v[204:205], v[20:21], v[0:1] op_sel_hi:[1,0]
	v_pk_mul_f32 v[202:203], v[248:249], v[202:203]
	v_pk_mul_f32 v[204:205], v[250:251], v[204:205]
	s_nop 0
	v_cvt_pk_bf16_f32 v198, v202, v203
	v_cvt_pk_bf16_f32 v199, v204, v205
	v_pk_mul_f32 v[202:203], v[28:29], v[0:1] op_sel_hi:[1,0]
	v_pk_mul_f32 v[204:205], v[22:23], v[0:1] op_sel_hi:[1,0]
	v_pk_mul_f32 v[202:203], v[176:177], v[202:203]
	v_pk_mul_f32 v[204:205], v[178:179], v[204:205]
	s_nop 0
	v_cvt_pk_bf16_f32 v200, v202, v203
	v_cvt_pk_bf16_f32 v201, v204, v205
	s_nop 1
	v_permlane32_swap_b32_e32 v198, v200
	v_permlane32_swap_b32_e32 v199, v201
	global_store_dwordx4 v[206:207], v[198:201], off offset:160
	v_pk_mul_f32 v[202:203], v[24:25], v[0:1] op_sel_hi:[1,0]
	v_pk_mul_f32 v[204:205], v[4:5], v[0:1] op_sel_hi:[1,0]
	v_pk_mul_f32 v[202:203], v[180:181], v[202:203]
	v_pk_mul_f32 v[204:205], v[182:183], v[204:205]
	s_nop 0
	v_cvt_pk_bf16_f32 v194, v202, v203
	v_cvt_pk_bf16_f32 v195, v204, v205
	v_pk_mul_f32 v[202:203], v[8:9], v[0:1] op_sel_hi:[1,0]
	v_pk_mul_f32 v[204:205], v[2:3], v[0:1] op_sel_hi:[1,0]
	v_pk_mul_f32 v[202:203], v[184:185], v[202:203]
	v_pk_mul_f32 v[204:205], v[186:187], v[204:205]
	s_nop 0
	v_cvt_pk_bf16_f32 v196, v202, v203
	v_cvt_pk_bf16_f32 v197, v204, v205
	s_nop 1
	v_permlane32_swap_b32_e32 v194, v196
	v_permlane32_swap_b32_e32 v195, v197
	global_store_dwordx4 v[206:207], v[194:197], off offset:192
	v_pk_mul_f32 v[202:203], v[6:7], v[0:1] op_sel_hi:[1,0]
	v_pk_mul_f32 v[204:205], v[66:67], v[0:1] op_sel_hi:[1,0]
	v_pk_mul_f32 v[202:203], v[188:189], v[202:203]
	v_pk_mul_f32 v[204:205], v[190:191], v[204:205]
	s_nop 0
	v_cvt_pk_bf16_f32 v198, v202, v203
	v_cvt_pk_bf16_f32 v199, v204, v205
	v_pk_mul_f32 v[202:203], v[68:69], v[0:1] op_sel_hi:[1,0]
	v_pk_mul_f32 v[204:205], v[16:17], v[0:1] op_sel_hi:[1,0]
	v_pk_mul_f32 v[202:203], v[166:167], v[202:203]
	v_pk_mul_f32 v[204:205], v[168:169], v[204:205]
	s_nop 0
	v_cvt_pk_bf16_f32 v200, v202, v203
	v_cvt_pk_bf16_f32 v201, v204, v205
	s_nop 1
	v_permlane32_swap_b32_e32 v198, v200
	v_permlane32_swap_b32_e32 v199, v201
	global_store_dwordx4 v[206:207], v[198:201], off offset:224
